# neighbourhood attention: fixed softmax shift (QK-norm bound + max of the head's bias table, fallback to running max), START uses it and the steady loop runs a copy without the row-max tree / rescale b
# speedup vs baseline: 1.0031x; 1.0031x over previous
; #define WAIT_BAR(N) asm volatile("s_waitcnt vmcnt(" #N ") lgkmcnt(0)\n\ts_barrier":::"memory")
;   #define WB(a,b) do{ if constexpr(DV2){WAIT_BAR(b);} else {WAIT_BAR(a);} }while(0)
;   #define DMA_K(t,slot) glds16(ksrc+(long)TMAP(t)*KVBLK*PQ,(unsigned)__builtin_amdgcn_readfirstlane(kdst+(slot)))
;   #define DMA_V(t,slot) glds16(vsrc+(long)TMAP(t)*KVBLK*PQ,(unsigned)__builtin_amdgcn_readfirstlane(vdst+(slot)))
;   #define DMA_V2(t,slot) do{ if constexpr(DV2) glds16(v2src+(long)TMAP(t)*KVBLK*PQ,(unsigned)__builtin_amdgcn_readfirstlane(v2dst+(slot))); }while(0)
;   #define ROT() do{sl_prev=sl_cur;sl_cur=sl_next;sl_next=(sl_next==(NSLOT-1)*SLOTB)?0:sl_next+SLOTB;}while(0)
;     ...
;   f32x16 pA0,pA1,pB0,pB1;
;   int sl_prev=0,sl_cur=0,sl_next=SLOTB;
;     ...
;   DMA_K(2,2*SLOTB);
;   WB(3,4);
;   qkt(pA0,pA1,Kbase,qr,NEGM,r32,hi);asm volatile("s_nop 15\n\ts_nop 7":"+v"(pA0),"+v"(pA1));CMASK(pA0,pA1,0);
;   START(pA0,pA1);
;   _Pragma("unroll") for(int r=0;r<16;++r)pA1[r]=__builtin_amdgcn_exp2f(pA1[r]);
;   WAIT_BAR(0);
;   DMA_K(3,0);DMA_V(1,SLOTB);DMA_V2(1,SLOTB);
;   ROT();
;   kload8(kf,kp0+sl_cur);
;   WB(2,3);
.Lfsk1_start_gen:
	s_nop 0
	v_add_f32_e32 v213, v1, v5
	v_sub_f32_e32 v6, v64, v5
	v_sub_f32_e32 v7, v48, v5
	v_sub_f32_e32 v8, v65, v5
	v_sub_f32_e32 v9, v49, v5
	v_sub_f32_e32 v10, v66, v5
	s_nop 0
	v_xor_b32_e32 v64, 0x80000000, v213
	v_sub_f32_e32 v11, v50, v5
	v_sub_f32_e32 v13, v67, v5
	v_sub_f32_e32 v17, v51, v5
	v_sub_f32_e32 v18, v68, v5
	v_sub_f32_e32 v19, v52, v5
	v_sub_f32_e32 v20, v69, v5
	v_sub_f32_e32 v21, v53, v5
	v_sub_f32_e32 v22, v70, v5
	v_sub_f32_e32 v23, v54, v5
	v_sub_f32_e32 v24, v71, v5
	v_sub_f32_e32 v25, v55, v5
	v_sub_f32_e32 v26, v72, v5
	v_sub_f32_e32 v27, v56, v5
	v_sub_f32_e32 v28, v73, v5
	v_sub_f32_e32 v29, v57, v5
	v_sub_f32_e32 v30, v74, v5
	v_sub_f32_e32 v31, v58, v5
	v_sub_f32_e32 v48, v75, v5
	v_sub_f32_e32 v49, v59, v5
	v_sub_f32_e32 v50, v76, v5
	v_sub_f32_e32 v51, v60, v5
	v_sub_f32_e32 v52, v77, v5
	v_sub_f32_e32 v53, v61, v5
	v_sub_f32_e32 v54, v78, v5
	v_sub_f32_e32 v55, v62, v5
	v_sub_f32_e32 v56, v79, v5
	v_sub_f32_e32 v5, v63, v5
	v_mov_b32_e32 v65, v64
	v_mov_b32_e32 v66, v64
	v_mov_b32_e32 v67, v64
	v_mov_b32_e32 v68, v64
	v_mov_b32_e32 v69, v64
	v_mov_b32_e32 v70, v64
	v_mov_b32_e32 v71, v64
	v_mov_b32_e32 v72, v64
	v_mov_b32_e32 v73, v64
	v_mov_b32_e32 v74, v64
	v_mov_b32_e32 v75, v64
	v_mov_b32_e32 v76, v64
	v_mov_b32_e32 v77, v64
	v_mov_b32_e32 v78, v64
	v_mov_b32_e32 v79, v64
	v_exp_f32_e32 v96, v6
	v_exp_f32_e32 v95, v5
	v_min_u32_e32 v6, 48, v4
	s_waitcnt vmcnt(0) lgkmcnt(0)
	s_barrier
	v_lshl_add_u64 v[4:5], v[2:3], 0, s[0:1]
	s_mov_b32 s10, m0
	s_mov_b32 m0, s33
	s_nop 0
	global_load_lds_dwordx4 v[4:5], off
	s_mov_b32 m0, s10
	v_lshl_add_u64 v[4:5], v[14:15], 0, s[86:87]
	s_add_i32 s10, s33, 0x8000
	s_mov_b32 s11, m0
	s_mov_b32 m0, s10
	s_nop 0
	global_load_lds_dwordx4 v[4:5], off
	s_mov_b32 m0, s11
	v_sub_u32_e32 v5, v217, v6
	v_cmp_gt_u32_e64 s[12:13], 16, v5
	v_or_b32_e32 v5, 32, v217
	v_sub_u32_e32 v5, v5, v6
	v_cmp_gt_u32_e64 s[14:15], 16, v5
	v_or_b32_e32 v5, 1, v217
	v_sub_u32_e32 v5, v5, v6
	v_cmp_gt_u32_e64 s[16:17], 16, v5
	v_or_b32_e32 v5, 33, v217
	v_sub_u32_e32 v5, v5, v6
	v_cmp_gt_u32_e64 s[18:19], 16, v5
	v_or_b32_e32 v5, 2, v217
	v_sub_u32_e32 v5, v5, v6
	v_cmp_gt_u32_e64 s[20:21], 16, v5
	v_or_b32_e32 v5, 34, v217
	v_sub_u32_e32 v5, v5, v6
	v_cmp_gt_u32_e64 s[22:23], 16, v5
	v_or_b32_e32 v5, 3, v217
	v_sub_u32_e32 v5, v5, v6
	v_cmp_gt_u32_e64 s[24:25], 16, v5
	v_or_b32_e32 v5, 35, v217
	v_sub_u32_e32 v5, v5, v6
	v_cmp_gt_u32_e64 s[26:27], 16, v5
	v_or_b32_e32 v5, 8, v217
	v_sub_u32_e32 v5, v5, v6
	v_cmp_gt_u32_e64 s[28:29], 16, v5
	v_or_b32_e32 v5, 40, v217
	v_sub_u32_e32 v5, v5, v6
	v_cmp_gt_u32_e64 s[30:31], 16, v5
	v_or_b32_e32 v5, 9, v217
	v_sub_u32_e32 v5, v5, v6
	v_cmp_gt_u32_e64 s[34:35], 16, v5
	v_or_b32_e32 v5, 41, v217
	v_sub_u32_e32 v5, v5, v6
	v_cmp_gt_u32_e64 s[36:37], 16, v5
	v_or_b32_e32 v5, 10, v217
	v_sub_u32_e32 v5, v5, v6
	v_cmp_gt_u32_e64 s[38:39], 16, v5
	v_or_b32_e32 v5, 42, v217
	v_sub_u32_e32 v5, v5, v6
	v_cmp_gt_u32_e64 s[40:41], 16, v5
	v_or_b32_e32 v5, 11, v217
	v_sub_u32_e32 v5, v5, v6
	v_cmp_gt_u32_e64 s[42:43], 16, v5
	v_or_b32_e32 v5, 43, v217
	v_sub_u32_e32 v5, v5, v6
	v_cmp_gt_u32_e64 s[44:45], 16, v5
	v_or_b32_e32 v5, 16, v217
	v_sub_u32_e32 v5, v5, v6
	v_cmp_gt_u32_e64 s[46:47], 16, v5
	v_or_b32_e32 v5, 48, v217
	v_sub_u32_e32 v5, v5, v6
	v_cmp_gt_u32_e64 s[48:49], 16, v5
	v_or_b32_e32 v5, 17, v217
	v_sub_u32_e32 v5, v5, v6
	v_cmp_gt_u32_e64 s[50:51], 16, v5
	v_or_b32_e32 v5, 49, v217
	v_sub_u32_e32 v5, v5, v6
	v_cmp_gt_u32_e64 s[52:53], 16, v5
	v_or_b32_e32 v5, 18, v217
	v_sub_u32_e32 v5, v5, v6
	v_cmp_gt_u32_e64 s[54:55], 16, v5
	v_or_b32_e32 v5, 50, v217
	v_sub_u32_e32 v5, v5, v6
	v_cmp_gt_u32_e64 s[56:57], 16, v5
	v_or_b32_e32 v5, 19, v217
	v_sub_u32_e32 v5, v5, v6
	v_cmp_gt_u32_e64 s[58:59], 16, v5
	v_or_b32_e32 v5, 51, v217
	v_sub_u32_e32 v5, v5, v6
	v_cmp_gt_u32_e64 s[60:61], 16, v5
	v_or_b32_e32 v5, 24, v217
	v_sub_u32_e32 v5, v5, v6
	v_cmp_gt_u32_e64 s[62:63], 16, v5
	v_or_b32_e32 v5, 56, v217
	v_sub_u32_e32 v5, v5, v6
	v_cmp_gt_u32_e64 s[64:65], 16, v5
	v_or_b32_e32 v5, 25, v217
	v_sub_u32_e32 v5, v5, v6
	v_exp_f32_e32 v100, v18
	v_exp_f32_e32 v101, v20
	v_exp_f32_e32 v102, v22
	v_exp_f32_e32 v103, v24
	v_exp_f32_e32 v104, v26
	v_exp_f32_e32 v105, v28
	v_exp_f32_e32 v84, v19
	v_exp_f32_e32 v85, v21
	v_exp_f32_e32 v86, v23
	v_exp_f32_e32 v87, v25
	v_exp_f32_e32 v88, v27
	v_exp_f32_e32 v89, v29
	ds_read_b128 v[180:183], v215 offset:8192
	ds_read_b128 v[156:159], v215 offset:8704
	ds_read_b128 v[152:155], v215 offset:10240
	ds_read_b128 v[148:151], v215 offset:10752
	ds_read_b128 v[144:147], v215 offset:12288
	ds_read_b128 v[26:29], v215 offset:12800
	ds_read_b128 v[22:25], v215 offset:14336
	ds_read_b128 v[18:21], v215 offset:14848
	v_cmp_gt_u32_e64 s[66:67], 16, v5
	v_or_b32_e32 v5, 57, v217
	v_sub_u32_e32 v5, v5, v6
	v_cmp_gt_u32_e64 s[68:69], 16, v5
	v_or_b32_e32 v5, 26, v217
	v_cmp_gt_u32_e64 s[10:11], 32, v202
	v_sub_u32_e32 v5, v5, v6
	v_exp_f32_e32 v80, v7
	v_writelane_b32 v255, s10, 19
	v_lshlrev_b32_e32 v4, 2, v204
	v_cmp_gt_u32_e64 s[70:71], 16, v5
	v_or_b32_e32 v5, 58, v217
	v_add_u32_e32 v7, s7, v209
	v_writelane_b32 v255, s11, 20
	v_add_u32_e32 v212, s85, v4
	v_sub_u32_e32 v5, v5, v6
	v_sub_u32_e32 v4, v7, v4
	s_mul_i32 s7, s89, 0x7c
	v_cmp_gt_u32_e64 s[72:73], 16, v5
	v_or_b32_e32 v5, 27, v217
	v_subrev_u32_e32 v4, s7, v4
	v_writelane_b32 v255, s74, 21
	s_lshl_b32 s7, s74, 7
	v_exp_f32_e32 v97, v8
	v_exp_f32_e32 v98, v10
	v_exp_f32_e32 v99, v13
	v_exp_f32_e32 v106, v30
	v_exp_f32_e32 v107, v48
	v_exp_f32_e32 v108, v50
	v_exp_f32_e32 v109, v52
	v_exp_f32_e32 v110, v54
	v_exp_f32_e32 v111, v56
	v_exp_f32_e32 v81, v9
	v_exp_f32_e32 v82, v11
	v_exp_f32_e32 v83, v17
	v_exp_f32_e32 v90, v31
	v_exp_f32_e32 v91, v49
	v_exp_f32_e32 v92, v51
	v_exp_f32_e32 v93, v53
	v_exp_f32_e32 v94, v55
	v_sub_u32_e32 v5, v5, v6
	s_and_b32 s7, s7, 0x80
	s_waitcnt vmcnt(2) lgkmcnt(0)
	s_barrier
	v_writelane_b32 v255, s75, 22
	v_subrev_u32_e32 v4, s7, v4
	v_cmp_gt_u32_e64 s[74:75], 16, v5
	v_or_b32_e32 v5, 59, v217
	v_sub_u32_e32 v5, v5, v6
	v_subrev_u32_e32 v192, s6, v4
	s_add_i32 s6, 0, 0x1622c
	v_mov_b64_e32 v[62:63], v[46:47]
	v_add_u32_e32 v193, s6, v192
	v_mov_b64_e32 v[60:61], v[44:45]
	v_mov_b64_e32 v[58:59], v[42:43]
	v_mov_b64_e32 v[56:57], v[40:41]
	v_mov_b64_e32 v[54:55], v[38:39]
	v_mov_b64_e32 v[52:53], v[36:37]
	v_mov_b64_e32 v[50:51], v[34:35]
	v_mov_b64_e32 v[48:49], v[32:33]
	v_cmp_gt_u32_e64 s[76:77], 16, v5
	v_readlane_b32 s99, v255, 43
	s_cmp_lg_u32 s99, 0
	s_cbranch_scc1 .Lfsk1_351

.LBB0_493:
	s_add_i32 s4, s94, 0x2000
	s_cmpk_lg_i32 s94, 0x4000
	s_cselect_b32 s5, s4, 0
	s_add_i32 s9, s9, 2
	v_add_u32_e32 v193, 0xf8, v193
	s_cmp_gt_u32 s92, 8
	v_lshl_add_u64 v[190:191], v[190:191], 0, s[96:97]
	s_cbranch_scc1 .LBB0_501
	s_mov_b32 s4, s91
	s_mov_b32 s93, s94
	s_mov_b32 s91, s5
	s_branch .LBB0_351
.Lfsk1_351:
	s_add_i32 s92, s9, -2
	v_add_u32_e32 v17, s4, v216
	ds_read_b64_tr_b16 v[184:185], v17 offset:24576
	ds_read_b64_tr_b16 v[186:187], v17 offset:25088
	s_waitcnt lgkmcnt(9)
	v_mfma_f32_32x32x16_bf16 v[128:143], v[180:183], v[176:179], v[64:79]
	v_add_f32_e32 v2, v96, v97
	v_cvt_pk_bf16_f32 v160, v96, v97
	v_add_f32_e32 v2, v98, v2
	v_cvt_pk_bf16_f32 v161, v98, v99
	v_add_f32_e32 v2, v99, v2
	v_add_f32_e32 v2, v100, v2
	v_add_f32_e32 v2, v101, v2
	ds_read_b64_tr_b16 v[180:181], v17 offset:28672
	ds_read_b64_tr_b16 v[182:183], v17 offset:29184
	s_waitcnt lgkmcnt(10)
	v_mfma_f32_32x32x16_bf16 v[112:127], v[156:159], v[176:179], v[64:79]
	v_add_f32_e32 v2, v102, v2
	v_cvt_pk_bf16_f32 v162, v100, v101
	v_add_f32_e32 v2, v103, v2
	v_cvt_pk_bf16_f32 v163, v102, v103
	v_add_f32_e32 v2, v104, v2
	v_add_f32_e32 v2, v105, v2
	ds_read_b64_tr_b16 v[96:97], v17 offset:25600
	ds_read_b64_tr_b16 v[98:99], v17 offset:26112
	s_waitcnt lgkmcnt(11)
	v_mfma_f32_32x32x16_bf16 v[128:143], v[152:155], v[172:175], v[128:143]
	v_add_f32_e32 v2, v106, v2
	v_cvt_pk_bf16_f32 v10, v104, v105
	v_add_f32_e32 v2, v107, v2
	v_cvt_pk_bf16_f32 v11, v106, v107
	v_add_f32_e32 v2, v108, v2
	v_add_f32_e32 v2, v109, v2
	ds_read_b64_tr_b16 v[100:101], v17 offset:29696
	ds_read_b64_tr_b16 v[102:103], v17 offset:30208
	s_waitcnt lgkmcnt(12)
	v_mfma_f32_32x32x16_bf16 v[112:127], v[148:151], v[172:175], v[112:127]
	v_add_f32_e32 v2, v110, v2
	v_cvt_pk_bf16_f32 v12, v108, v109
	v_add_f32_e32 v2, v111, v2
	v_cvt_pk_bf16_f32 v13, v110, v111
	v_add_f32_e32 v2, v80, v2
	v_add_f32_e32 v2, v81, v2
	ds_read_b64_tr_b16 v[104:105], v17 offset:26624
	ds_read_b64_tr_b16 v[106:107], v17 offset:27136
	s_waitcnt lgkmcnt(13)
	v_mfma_f32_32x32x16_bf16 v[128:143], v[144:147], v[168:171], v[128:143]
	v_add_f32_e32 v2, v82, v2
	v_cvt_pk_bf16_f32 v6, v80, v81
	v_add_f32_e32 v2, v83, v2
	v_cvt_pk_bf16_f32 v7, v82, v83
	v_add_f32_e32 v2, v84, v2
	v_add_f32_e32 v2, v85, v2
	ds_read_b64_tr_b16 v[80:81], v17 offset:30720
	ds_read_b64_tr_b16 v[82:83], v17 offset:31232
	s_waitcnt lgkmcnt(14)
	v_mfma_f32_32x32x16_bf16 v[112:127], v[26:29], v[168:171], v[112:127]
	v_add_f32_e32 v2, v86, v2
	v_cvt_pk_bf16_f32 v8, v84, v85
	v_add_f32_e32 v2, v87, v2
	v_cvt_pk_bf16_f32 v9, v86, v87
	v_add_f32_e32 v2, v88, v2
	v_add_f32_e32 v2, v89, v2
	ds_read_b64_tr_b16 v[84:85], v17 offset:27648
	ds_read_b64_tr_b16 v[86:87], v17 offset:28160
	s_waitcnt lgkmcnt(14)
	v_mfma_f32_32x32x16_bf16 v[128:143], v[22:25], v[164:167], v[128:143]
	v_add_f32_e32 v2, v90, v2
	v_cvt_pk_bf16_f32 v3, v90, v91
	v_add_f32_e32 v2, v91, v2
	v_add_f32_e32 v2, v92, v2
	v_add_f32_e32 v22, v93, v2
	v_cvt_pk_bf16_f32 v2, v88, v89
	ds_read_b64_tr_b16 v[88:89], v17 offset:31744
	ds_read_b64_tr_b16 v[90:91], v17 offset:32256
	v_mfma_f32_32x32x16_bf16 v[112:127], v[18:21], v[164:167], v[112:127]
	v_add_f32_e32 v4, v94, v22
	v_cvt_pk_bf16_f32 v5, v94, v95
	v_add_f32_e32 v4, v95, v4
	v_add_f32_e32 v108, 0, v4
	v_cvt_pk_bf16_f32 v4, v92, v93
	s_add_i32 s6, s9, -1
	s_add_i32 s4, s93, s33
	s_add_i32 s7, s6, s8
	s_cmp_gt_u32 s92, 2
	s_cselect_b64 s[10:11], -1, 0
	s_mov_b32 s5, m0
	s_mov_b32 m0, s4
	s_nop 0
	global_load_lds_dwordx4 v[190:191], off
	s_mov_b32 m0, s5
	s_and_b64 s[4:5], s[10:11], exec
	s_cselect_b32 s82, s7, s6
	s_lshl_b64 s[4:5], s[82:83], 13
	v_lshl_add_u64 v[18:19], v[14:15], 0, s[4:5]
	s_add_i32 s4, s91, s88
	s_mov_b32 s5, m0
	s_mov_b32 m0, s4
	s_nop 0
	global_load_lds_dwordx4 v[18:19], off
	s_mov_b32 m0, s5
	s_cmp_lt_u32 s92, 4
	s_cbranch_scc1 .Lfsk1_419
	s_add_i32 s4, s90, s9
	s_add_i32 s4, s4, -6
	s_cmp_gt_u32 s4, 7
	s_cbranch_scc1 .Lfsk1_418
	ds_read_b32 v18, v193
	ds_read_b32 v17, v193 offset:128
	ds_read_b32 v20, v193 offset:4
	ds_read_b32 v19, v193 offset:132
	ds_read_b32 v22, v193 offset:8
	ds_read_b32 v21, v193 offset:136
	ds_read_b32 v24, v193 offset:12
	ds_read_b32 v23, v193 offset:140
	ds_read_b32 v26, v193 offset:32
	ds_read_b32 v25, v193 offset:160
	ds_read_b32 v28, v193 offset:36
	ds_read_b32 v27, v193 offset:164
	ds_read_b32 v30, v193 offset:40
	ds_read_b32 v29, v193 offset:168
	ds_read_b32 v92, v193 offset:44
	ds_read_b32 v31, v193 offset:172
	ds_read_b32 v94, v193 offset:64
	ds_read_b32 v93, v193 offset:192
	ds_read_b32 v109, v193 offset:68
	ds_read_b32 v95, v193 offset:196
	ds_read_b32 v111, v193 offset:72
	ds_read_b32 v110, v193 offset:200
	ds_read_b32 v145, v193 offset:76
	ds_read_b32 v144, v193 offset:204
	ds_read_b32 v147, v193 offset:96
	ds_read_b32 v146, v193 offset:224
	ds_read_b32 v149, v193 offset:100
	ds_read_b32 v148, v193 offset:228
	ds_read_b32 v151, v193 offset:104
	ds_read_b32 v150, v193 offset:232
	ds_read_b32 v153, v193 offset:108
	ds_read_b32 v152, v193 offset:236
	s_waitcnt lgkmcnt(0)
	v_add_f32_e32 v17, v112, v17
	v_cndmask_b32_e64 v112, v16, v17, s[14:15]
	v_add_f32_e32 v17, v129, v20
	v_cndmask_b32_e64 v129, v16, v17, s[16:17]
	v_add_f32_e32 v17, v113, v19
	v_cndmask_b32_e64 v113, v16, v17, s[18:19]
	v_add_f32_e32 v17, v130, v22
	v_cndmask_b32_e64 v130, v16, v17, s[20:21]
	v_add_f32_e32 v17, v114, v21
	v_cndmask_b32_e64 v114, v16, v17, s[22:23]
	v_add_f32_e32 v17, v131, v24
	v_cndmask_b32_e64 v131, v16, v17, s[24:25]
	v_add_f32_e32 v17, v115, v23
	v_cndmask_b32_e64 v115, v16, v17, s[26:27]
	v_add_f32_e32 v17, v132, v26
	v_cndmask_b32_e64 v132, v16, v17, s[28:29]
	v_add_f32_e32 v17, v116, v25
	v_cndmask_b32_e64 v116, v16, v17, s[30:31]
	v_add_f32_e32 v17, v133, v28
	v_cndmask_b32_e64 v133, v16, v17, s[34:35]
	v_add_f32_e32 v17, v117, v27
	v_cndmask_b32_e64 v117, v16, v17, s[36:37]
	v_add_f32_e32 v17, v134, v30
	v_cndmask_b32_e64 v134, v16, v17, s[38:39]
	v_add_f32_e32 v17, v118, v29
	v_cndmask_b32_e64 v118, v16, v17, s[40:41]
	v_add_f32_e32 v17, v135, v92
	v_cndmask_b32_e64 v135, v16, v17, s[42:43]
	v_add_f32_e32 v17, v119, v31
	v_cndmask_b32_e64 v119, v16, v17, s[44:45]
	v_add_f32_e32 v17, v136, v94
	v_cndmask_b32_e64 v136, v16, v17, s[46:47]
	v_add_f32_e32 v17, v120, v93
	v_cndmask_b32_e64 v120, v16, v17, s[48:49]
	v_add_f32_e32 v17, v137, v109
	v_cndmask_b32_e64 v137, v16, v17, s[50:51]
	v_add_f32_e32 v17, v121, v95
	v_cndmask_b32_e64 v121, v16, v17, s[52:53]
	v_add_f32_e32 v17, v138, v111
	v_cndmask_b32_e64 v138, v16, v17, s[54:55]
	v_add_f32_e32 v17, v122, v110
	v_cndmask_b32_e64 v122, v16, v17, s[56:57]
	v_add_f32_e32 v17, v139, v145
	v_cndmask_b32_e64 v139, v16, v17, s[58:59]
	v_add_f32_e32 v17, v123, v144
	v_cndmask_b32_e64 v123, v16, v17, s[60:61]
	v_add_f32_e32 v17, v140, v147
	v_cndmask_b32_e64 v140, v16, v17, s[62:63]
	v_add_f32_e32 v17, v124, v146
	v_cndmask_b32_e64 v124, v16, v17, s[64:65]
	v_add_f32_e32 v17, v141, v149
	v_cndmask_b32_e64 v141, v16, v17, s[66:67]
	v_add_f32_e32 v17, v125, v148
	v_cndmask_b32_e64 v125, v16, v17, s[68:69]
	v_add_f32_e32 v17, v142, v151
	v_cndmask_b32_e64 v142, v16, v17, s[70:71]
	v_add_f32_e32 v17, v126, v150
	v_cndmask_b32_e64 v126, v16, v17, s[72:73]
	v_add_f32_e32 v17, v143, v153
	v_add_f32_e32 v18, v128, v18
	v_cndmask_b32_e64 v143, v16, v17, s[74:75]
	v_add_f32_e32 v17, v127, v152
	v_cndmask_b32_e64 v128, v16, v18, s[12:13]
	v_cndmask_b32_e64 v127, v16, v17, s[76:77]
	s_branch .Lfsk1_419

;   #define WB(a,b) do{ if constexpr(DV2){WAIT_BAR(b);} else {WAIT_BAR(a);} }while(0)
;   #define RESC() do{ if(resc){ asm volatile("s_waitcnt lgkmcnt(0)":::"memory"); \
;       _Pragma("unroll") for(int d_=0;d_<ND;++d_) _Pragma("unroll") for(int r=0;r<16;++r)o[d_][r]*=wsf[crow(r,hi)]; } }while(0)
;   #define ROT() do{sl_prev=sl_cur;sl_cur=sl_next;sl_next=(sl_next==(NSLOT-1)*SLOTB)?0:sl_next+SLOTB;}while(0)
;     ...
;   int t=1;
;   for(;t+5<NT;t+=2){
;     STEP(pB0,pB1,pA0,pA1,t,true,true,true);     WB(2,3); RESC(); ROT();
;     STEP(pA0,pA1,pB0,pB1,t+1,true,true,true);   WB(2,3); RESC(); ROT();
;   }
.Lfsk1_419:
	v_add_f32_e32 v194, v218, v108
.Lfsk1_420:
	s_waitcnt lgkmcnt(14)
	v_mfma_f32_32x32x16_bf16 v[32:47], v[160:163], v[184:187], v[32:47]
	v_exp_f32_e32 v128, v128
	v_exp_f32_e32 v129, v129
	v_exp_f32_e32 v130, v130
	v_exp_f32_e32 v131, v131
	s_waitcnt lgkmcnt(12)
	v_mfma_f32_32x32x16_bf16 v[48:63], v[160:163], v[180:183], v[48:63]
	v_exp_f32_e32 v132, v132
	v_exp_f32_e32 v133, v133
	v_exp_f32_e32 v134, v134
	v_exp_f32_e32 v135, v135
	v_add_u32_e32 v17, s91, v215
	ds_read_b128 v[92:95], v17
	ds_read_b128 v[180:183], v17 offset:512
	s_waitcnt lgkmcnt(12)
	v_mfma_f32_32x32x16_bf16 v[32:47], v[10:13], v[96:99], v[32:47]
	v_exp_f32_e32 v136, v136
	v_exp_f32_e32 v137, v137
	v_exp_f32_e32 v138, v138
	v_exp_f32_e32 v139, v139
	ds_read_b128 v[184:187], v17 offset:2048
	ds_read_b128 v[156:159], v17 offset:2560
	s_waitcnt lgkmcnt(12)
	v_mfma_f32_32x32x16_bf16 v[48:63], v[10:13], v[100:103], v[48:63]
	v_exp_f32_e32 v140, v140
	v_exp_f32_e32 v141, v141
	v_exp_f32_e32 v142, v142
	v_exp_f32_e32 v143, v143
	ds_read_b128 v[152:155], v17 offset:4096
	ds_read_b128 v[26:29], v17 offset:4608
	s_waitcnt lgkmcnt(12)
	v_mfma_f32_32x32x16_bf16 v[32:47], v[6:9], v[104:107], v[32:47]
	v_exp_f32_e32 v112, v112
	v_exp_f32_e32 v113, v113
	v_exp_f32_e32 v114, v114
	v_exp_f32_e32 v115, v115
	ds_read_b128 v[22:25], v17 offset:6144
	ds_read_b128 v[18:21], v17 offset:6656
	s_waitcnt lgkmcnt(12)
	v_mfma_f32_32x32x16_bf16 v[48:63], v[6:9], v[80:83], v[48:63]
	v_exp_f32_e32 v116, v116
	v_exp_f32_e32 v117, v117
	v_exp_f32_e32 v118, v118
	v_exp_f32_e32 v119, v119
	s_waitcnt lgkmcnt(10)
	v_mfma_f32_32x32x16_bf16 v[32:47], v[2:5], v[84:87], v[32:47]
	v_exp_f32_e32 v120, v120
	v_exp_f32_e32 v121, v121
	v_exp_f32_e32 v122, v122
	v_exp_f32_e32 v123, v123
	s_waitcnt lgkmcnt(8)
	v_mfma_f32_32x32x16_bf16 v[48:63], v[2:5], v[88:91], v[48:63]
	v_exp_f32_e32 v124, v124
	v_exp_f32_e32 v125, v125
	v_exp_f32_e32 v126, v126
	v_exp_f32_e32 v127, v127
	s_waitcnt vmcnt(2) lgkmcnt(0)
	s_barrier
.Lfsk1_422:
	s_add_i32 s4, s91, 0x2000
	s_cmpk_lg_i32 s91, 0x4000
	s_cselect_b32 s94, s4, 0
	v_add_u32_e32 v17, s93, v216
	ds_read_b64_tr_b16 v[148:149], v17 offset:24576
	ds_read_b64_tr_b16 v[150:151], v17 offset:25088
	s_waitcnt lgkmcnt(9)
	v_mfma_f32_32x32x16_bf16 v[96:111], v[92:95], v[176:179], v[64:79]
	v_add_f32_e32 v2, v128, v129
	v_cvt_pk_bf16_f32 v160, v128, v129
	v_add_f32_e32 v2, v130, v2
	v_cvt_pk_bf16_f32 v161, v130, v131
	v_add_f32_e32 v2, v131, v2
	v_add_f32_e32 v2, v132, v2
	v_add_f32_e32 v2, v133, v2
	ds_read_b64_tr_b16 v[144:145], v17 offset:28672
	ds_read_b64_tr_b16 v[146:147], v17 offset:29184
	s_waitcnt lgkmcnt(10)
	v_mfma_f32_32x32x16_bf16 v[80:95], v[180:183], v[176:179], v[64:79]
	v_add_f32_e32 v2, v134, v2
	v_cvt_pk_bf16_f32 v162, v132, v133
	v_add_f32_e32 v2, v135, v2
	v_cvt_pk_bf16_f32 v163, v134, v135
	v_add_f32_e32 v2, v136, v2
	v_add_f32_e32 v2, v137, v2
	ds_read_b64_tr_b16 v[128:129], v17 offset:25600
	ds_read_b64_tr_b16 v[130:131], v17 offset:26112
	s_waitcnt lgkmcnt(11)
	v_mfma_f32_32x32x16_bf16 v[96:111], v[184:187], v[172:175], v[96:111]
	v_add_f32_e32 v2, v138, v2
	v_cvt_pk_bf16_f32 v10, v136, v137
	v_add_f32_e32 v2, v139, v2
	v_cvt_pk_bf16_f32 v11, v138, v139
	v_add_f32_e32 v2, v140, v2
	v_add_f32_e32 v2, v141, v2
	ds_read_b64_tr_b16 v[132:133], v17 offset:29696
	ds_read_b64_tr_b16 v[134:135], v17 offset:30208
	s_waitcnt lgkmcnt(12)
	v_mfma_f32_32x32x16_bf16 v[80:95], v[156:159], v[172:175], v[80:95]
	v_add_f32_e32 v2, v142, v2
	v_cvt_pk_bf16_f32 v12, v140, v141
	v_add_f32_e32 v2, v143, v2
	v_cvt_pk_bf16_f32 v13, v142, v143
	v_add_f32_e32 v2, v112, v2
	v_add_f32_e32 v2, v113, v2
	ds_read_b64_tr_b16 v[136:137], v17 offset:26624
	ds_read_b64_tr_b16 v[138:139], v17 offset:27136
	s_waitcnt lgkmcnt(13)
	v_mfma_f32_32x32x16_bf16 v[96:111], v[152:155], v[168:171], v[96:111]
	v_add_f32_e32 v2, v114, v2
	v_cvt_pk_bf16_f32 v6, v112, v113
	v_add_f32_e32 v2, v115, v2
	v_cvt_pk_bf16_f32 v7, v114, v115
	v_add_f32_e32 v2, v116, v2
	v_add_f32_e32 v2, v117, v2
	ds_read_b64_tr_b16 v[112:113], v17 offset:30720
	ds_read_b64_tr_b16 v[114:115], v17 offset:31232
	s_waitcnt lgkmcnt(14)
	v_mfma_f32_32x32x16_bf16 v[80:95], v[26:29], v[168:171], v[80:95]
	v_add_f32_e32 v2, v118, v2
	v_cvt_pk_bf16_f32 v8, v116, v117
	v_add_f32_e32 v2, v119, v2
	v_cvt_pk_bf16_f32 v9, v118, v119
	v_add_f32_e32 v2, v120, v2
	v_add_f32_e32 v2, v121, v2
	ds_read_b64_tr_b16 v[116:117], v17 offset:27648
	ds_read_b64_tr_b16 v[118:119], v17 offset:28160
	s_waitcnt lgkmcnt(14)
	v_mfma_f32_32x32x16_bf16 v[96:111], v[22:25], v[164:167], v[96:111]
	v_add_f32_e32 v2, v122, v2
	v_cvt_pk_bf16_f32 v3, v122, v123
	v_add_f32_e32 v2, v123, v2
	v_add_f32_e32 v2, v124, v2
	v_add_f32_e32 v22, v125, v2
	v_cvt_pk_bf16_f32 v2, v120, v121
	ds_read_b64_tr_b16 v[120:121], v17 offset:31744
	ds_read_b64_tr_b16 v[122:123], v17 offset:32256
	v_mfma_f32_32x32x16_bf16 v[80:95], v[18:21], v[164:167], v[80:95]
	v_add_f32_e32 v4, v126, v22
	v_cvt_pk_bf16_f32 v5, v126, v127
	v_add_f32_e32 v4, v127, v4
	v_add_f32_e32 v140, 0, v4
	v_cvt_pk_bf16_f32 v4, v124, v125
	s_add_i32 s4, s91, s33
	v_lshl_add_u64 v[18:19], v[190:191], 0, s[86:87]
	s_mov_b32 s5, m0
	s_mov_b32 m0, s4
	s_nop 0
	global_load_lds_dwordx4 v[18:19], off
	s_mov_b32 m0, s5
	s_cmp_gt_u32 s92, 1
	v_readlane_b32 s4, v255, 11
	s_cselect_b32 s4, s4, 0
	s_add_i32 s82, s4, s9
	s_lshl_b64 s[4:5], s[82:83], 13
	v_lshl_add_u64 v[18:19], v[14:15], 0, s[4:5]
	s_add_i32 s4, s94, s88
	s_mov_b32 s5, m0
	s_mov_b32 m0, s4
	s_nop 0
	global_load_lds_dwordx4 v[18:19], off
	s_mov_b32 m0, s5
	s_andn2_b64 vcc, exec, s[10:11]
	s_cbranch_vccnz .Lfsk1_490
	s_add_i32 s4, s90, s9
	s_add_i32 s4, s4, -5
	s_cmp_gt_u32 s4, 7
	s_cbranch_scc1 .Lfsk1_489
	ds_read_b32 v18, v193 offset:124
	ds_read_b32 v17, v193 offset:252
	ds_read_b32 v20, v193 offset:128
	ds_read_b32 v19, v193 offset:256
	ds_read_b32 v22, v193 offset:132
	ds_read_b32 v21, v193 offset:260
	ds_read_b32 v24, v193 offset:136
	ds_read_b32 v23, v193 offset:264
	ds_read_b32 v26, v193 offset:156
	ds_read_b32 v25, v193 offset:284
	ds_read_b32 v28, v193 offset:160
	ds_read_b32 v27, v193 offset:288
	ds_read_b32 v30, v193 offset:164
	ds_read_b32 v29, v193 offset:292
	ds_read_b32 v124, v193 offset:168
	ds_read_b32 v31, v193 offset:296
	ds_read_b32 v126, v193 offset:188
	ds_read_b32 v125, v193 offset:316
	ds_read_b32 v141, v193 offset:192
	ds_read_b32 v127, v193 offset:320
	ds_read_b32 v143, v193 offset:196
	ds_read_b32 v142, v193 offset:324
	ds_read_b32 v153, v193 offset:200
	ds_read_b32 v152, v193 offset:328
	ds_read_b32 v155, v193 offset:220
	ds_read_b32 v154, v193 offset:348
	ds_read_b32 v157, v193 offset:224
	ds_read_b32 v156, v193 offset:352
	ds_read_b32 v159, v193 offset:228
	ds_read_b32 v158, v193 offset:356
	ds_read_b32 v181, v193 offset:232
	ds_read_b32 v180, v193 offset:360
	s_waitcnt lgkmcnt(0)
	v_add_f32_e32 v17, v80, v17
	v_cndmask_b32_e64 v80, v16, v17, s[14:15]
	v_add_f32_e32 v17, v97, v20
	v_cndmask_b32_e64 v97, v16, v17, s[16:17]
	v_add_f32_e32 v17, v81, v19
	v_cndmask_b32_e64 v81, v16, v17, s[18:19]
	v_add_f32_e32 v17, v98, v22
	v_cndmask_b32_e64 v98, v16, v17, s[20:21]
	v_add_f32_e32 v17, v82, v21
	v_cndmask_b32_e64 v82, v16, v17, s[22:23]
	v_add_f32_e32 v17, v99, v24
	v_cndmask_b32_e64 v99, v16, v17, s[24:25]
	v_add_f32_e32 v17, v83, v23
	v_cndmask_b32_e64 v83, v16, v17, s[26:27]
	v_add_f32_e32 v17, v100, v26
	v_cndmask_b32_e64 v100, v16, v17, s[28:29]
	v_add_f32_e32 v17, v84, v25
	v_cndmask_b32_e64 v84, v16, v17, s[30:31]
	v_add_f32_e32 v17, v101, v28
	v_cndmask_b32_e64 v101, v16, v17, s[34:35]
	v_add_f32_e32 v17, v85, v27
	v_cndmask_b32_e64 v85, v16, v17, s[36:37]
	v_add_f32_e32 v17, v102, v30
	v_cndmask_b32_e64 v102, v16, v17, s[38:39]
	v_add_f32_e32 v17, v86, v29
	v_cndmask_b32_e64 v86, v16, v17, s[40:41]
	v_add_f32_e32 v17, v103, v124
	v_cndmask_b32_e64 v103, v16, v17, s[42:43]
	v_add_f32_e32 v17, v87, v31
	v_cndmask_b32_e64 v87, v16, v17, s[44:45]
	v_add_f32_e32 v17, v104, v126
	v_cndmask_b32_e64 v104, v16, v17, s[46:47]
	v_add_f32_e32 v17, v88, v125
	v_cndmask_b32_e64 v88, v16, v17, s[48:49]
	v_add_f32_e32 v17, v105, v141
	v_cndmask_b32_e64 v105, v16, v17, s[50:51]
	v_add_f32_e32 v17, v89, v127
	v_cndmask_b32_e64 v89, v16, v17, s[52:53]
	v_add_f32_e32 v17, v106, v143
	v_cndmask_b32_e64 v106, v16, v17, s[54:55]
	v_add_f32_e32 v17, v90, v142
	v_cndmask_b32_e64 v90, v16, v17, s[56:57]
	v_add_f32_e32 v17, v107, v153
	v_cndmask_b32_e64 v107, v16, v17, s[58:59]
	v_add_f32_e32 v17, v91, v152
	v_cndmask_b32_e64 v91, v16, v17, s[60:61]
	v_add_f32_e32 v17, v108, v155
	v_cndmask_b32_e64 v108, v16, v17, s[62:63]
	v_add_f32_e32 v17, v92, v154
	v_cndmask_b32_e64 v92, v16, v17, s[64:65]
	v_add_f32_e32 v17, v109, v157
	v_cndmask_b32_e64 v109, v16, v17, s[66:67]
	v_add_f32_e32 v17, v93, v156
	v_cndmask_b32_e64 v93, v16, v17, s[68:69]
	v_add_f32_e32 v17, v110, v159
	v_cndmask_b32_e64 v110, v16, v17, s[70:71]
	v_add_f32_e32 v17, v94, v158
	v_cndmask_b32_e64 v94, v16, v17, s[72:73]
	v_add_f32_e32 v17, v111, v181
	v_add_f32_e32 v18, v96, v18
	v_cndmask_b32_e64 v111, v16, v17, s[74:75]
	v_add_f32_e32 v17, v95, v180
	v_cndmask_b32_e64 v96, v16, v18, s[12:13]
	v_cndmask_b32_e64 v95, v16, v17, s[76:77]
	s_branch .Lfsk1_490

;   #define WB(a,b) do{ if constexpr(DV2){WAIT_BAR(b);} else {WAIT_BAR(a);} }while(0)
;   #define RESC() do{ if(resc){ asm volatile("s_waitcnt lgkmcnt(0)":::"memory"); \
;       _Pragma("unroll") for(int d_=0;d_<ND;++d_) _Pragma("unroll") for(int r=0;r<16;++r)o[d_][r]*=wsf[crow(r,hi)]; } }while(0)
;   #define ROT() do{sl_prev=sl_cur;sl_cur=sl_next;sl_next=(sl_next==(NSLOT-1)*SLOTB)?0:sl_next+SLOTB;}while(0)
;     ...
;   int t=1;
;   for(;t+5<NT;t+=2){
;     STEP(pB0,pB1,pA0,pA1,t,true,true,true);     WB(2,3); RESC(); ROT();
;     STEP(pA0,pA1,pB0,pB1,t+1,true,true,true);   WB(2,3); RESC(); ROT();
;   }
.Lfsk1_490:
	v_add_f32_e32 v218, v194, v140
.Lfsk1_491:
	s_waitcnt lgkmcnt(14)
	v_mfma_f32_32x32x16_bf16 v[32:47], v[160:163], v[148:151], v[32:47]
	v_exp_f32_e32 v96, v96
	v_exp_f32_e32 v97, v97
	v_exp_f32_e32 v98, v98
	v_exp_f32_e32 v99, v99
	s_waitcnt lgkmcnt(12)
	v_mfma_f32_32x32x16_bf16 v[48:63], v[160:163], v[144:147], v[48:63]
	v_exp_f32_e32 v100, v100
	v_exp_f32_e32 v101, v101
	v_exp_f32_e32 v102, v102
	v_exp_f32_e32 v103, v103
	v_add_u32_e32 v17, s94, v215
	ds_read_b128 v[180:183], v17
	ds_read_b128 v[156:159], v17 offset:512
	s_waitcnt lgkmcnt(12)
	v_mfma_f32_32x32x16_bf16 v[32:47], v[10:13], v[128:131], v[32:47]
	v_exp_f32_e32 v104, v104
	v_exp_f32_e32 v105, v105
	v_exp_f32_e32 v106, v106
	v_exp_f32_e32 v107, v107
	ds_read_b128 v[152:155], v17 offset:2048
	ds_read_b128 v[148:151], v17 offset:2560
	s_waitcnt lgkmcnt(12)
	v_mfma_f32_32x32x16_bf16 v[48:63], v[10:13], v[132:135], v[48:63]
	v_exp_f32_e32 v108, v108
	v_exp_f32_e32 v109, v109
	v_exp_f32_e32 v110, v110
	v_exp_f32_e32 v111, v111
	ds_read_b128 v[144:147], v17 offset:4096
	ds_read_b128 v[26:29], v17 offset:4608
	s_waitcnt lgkmcnt(12)
	v_mfma_f32_32x32x16_bf16 v[32:47], v[6:9], v[136:139], v[32:47]
	v_exp_f32_e32 v80, v80
	v_exp_f32_e32 v81, v81
	v_exp_f32_e32 v82, v82
	v_exp_f32_e32 v83, v83
	ds_read_b128 v[22:25], v17 offset:6144
	ds_read_b128 v[18:21], v17 offset:6656
	s_waitcnt lgkmcnt(12)
	v_mfma_f32_32x32x16_bf16 v[48:63], v[6:9], v[112:115], v[48:63]
	v_exp_f32_e32 v84, v84
	v_exp_f32_e32 v85, v85
	v_exp_f32_e32 v86, v86
	v_exp_f32_e32 v87, v87
	s_waitcnt lgkmcnt(10)
	v_mfma_f32_32x32x16_bf16 v[32:47], v[2:5], v[116:119], v[32:47]
	v_exp_f32_e32 v88, v88
	v_exp_f32_e32 v89, v89
	v_exp_f32_e32 v90, v90
	v_exp_f32_e32 v91, v91
	s_waitcnt lgkmcnt(8)
	v_mfma_f32_32x32x16_bf16 v[48:63], v[2:5], v[120:123], v[48:63]
	v_exp_f32_e32 v92, v92
	v_exp_f32_e32 v93, v93
	v_exp_f32_e32 v94, v94
	v_exp_f32_e32 v95, v95
	s_waitcnt vmcnt(2) lgkmcnt(0)
	s_barrier
.Lfsk1_493:
	s_add_i32 s4, s94, 0x2000
	s_cmpk_lg_i32 s94, 0x4000
	s_cselect_b32 s5, s4, 0
	s_add_i32 s9, s9, 2
	v_add_u32_e32 v193, 0xf8, v193
	s_cmp_gt_u32 s92, 8
	v_lshl_add_u64 v[190:191], v[190:191], 0, s[96:97]
	s_cbranch_scc1 .LBB0_501
	s_mov_b32 s4, s91
	s_mov_b32 s93, s94
	s_mov_b32 s91, s5
	s_branch .Lfsk1_351
